# c55 + token-0 memory-attention: the 34 phase-1 row loads are issued before the q-staging wait and barrier (q load and row loads overlap), both instances; hot-loop offsets preserved
# baseline (speedup 1.0000x reference)
; #define LAS __attribute__((address_space(3)))
; DI void tok0_mix_dil(ldsp lds, const Params& p, const float* P, float* BRo, int task, int tid, int wid, int lane) {
;     const int b = task >> 2, hm = task & 3;
;     const float* pr = P + (size_t)b * 8192;
;     LAS float* OUT = (LAS float*)(lds + 65536); LAS float* S18 = OUT + 64;
;     tok0_mem(lds, pr + DB_QM + hm * 64, p.mem + (size_t)b * 256 * 1024, p.mem_norm_w, p.w_memkv + (size_t)1024 * 512, hm, OUT, tid, wid, lane);
; __global__ void __launch_bounds__(NTHREADS, 2) megak(Params p) {
;     ...
;             if (L == 0) {
;                 __syncthreads();
;                 for (int t = blockIdx.x; t < BATCH * 4; t += gridDim.x) tok0_mix_dil(lds, p, T0P, T0BR, t, tid, wid, lane);
.LBB0_91:
	s_andn2_b64 vcc, exec, s[40:41]
	s_cbranch_vccnz .LBB0_126
	v_readlane_b32 s14, v251, 45
	v_readlane_b32 s15, v251, 46
	s_andn2_b64 vcc, exec, s[14:15]
	s_waitcnt vmcnt(0) lgkmcnt(0)
	s_barrier
	s_cbranch_vccnz .LBB0_126
	v_mov_b32_e32 v33, v12
	v_mov_b64_e32 v[30:31], v[32:33]
	v_ashrrev_i32_e32 v33, 31, v32
	v_lshlrev_b64 v[0:1], 11, v[32:33]
	s_mov_b64 s[14:15], 0x100000
	v_lshl_add_u64 v[78:79], v[0:1], 0, s[14:15]
	v_and_b32_e32 v0, 64, v233
	v_add_u32_e32 v0, 64, v0
	v_xor_b32_e32 v1, 32, v233
	v_cmp_lt_i32_e32 vcc, v1, v0
	s_lshl_b32 s22, s16, 5
	v_readlane_b32 s0, v255, 14
	v_cndmask_b32_e32 v1, v233, v1, vcc
	v_lshlrev_b32_e32 v95, 2, v1
	v_xor_b32_e32 v1, 16, v233
	v_cmp_lt_i32_e32 vcc, v1, v0
	s_cmp_lt_u32 s0, 64
	v_lshlrev_b32_e32 v3, 2, v32
	v_cndmask_b32_e32 v1, v233, v1, vcc
	v_lshlrev_b32_e32 v96, 2, v1
	v_xor_b32_e32 v1, 8, v233
	v_cmp_lt_i32_e32 vcc, v1, v0
	v_readlane_b32 s48, v254, 15
	s_cselect_b64 s[46:47], -1, 0
	v_cndmask_b32_e32 v1, v233, v1, vcc
	v_lshlrev_b32_e32 v97, 2, v1
	v_xor_b32_e32 v1, 4, v233
	v_cmp_lt_i32_e32 vcc, v1, v0
	s_add_i32 s0, 0, 0x10000
	v_readlane_b32 s49, v254, 16
	v_cndmask_b32_e32 v1, v233, v1, vcc
	v_lshlrev_b32_e32 v98, 2, v1
	v_xor_b32_e32 v1, 2, v233
	v_cmp_lt_i32_e32 vcc, v1, v0
	v_add_u32_e32 v102, s0, v3
	s_cmp_lt_i32 s16, 18
	v_cndmask_b32_e32 v1, v233, v1, vcc
	v_lshlrev_b32_e32 v99, 2, v1
	v_xor_b32_e32 v1, 1, v233
	v_cmp_lt_i32_e32 vcc, v1, v0
	s_movk_i32 s0, 0x300
	v_lshlrev_b32_e32 v4, 4, v32
	v_cndmask_b32_e32 v0, v233, v1, vcc
	v_ashrrev_i32_e32 v1, 8, v32
	v_lshlrev_b32_e32 v100, 2, v0
	v_lshlrev_b32_e32 v0, 7, v1
	s_cselect_b64 s[48:49], -1, 0
	v_cmp_gt_i32_e64 s[42:43], s0, v32
	s_add_i32 s0, 0, 0x1000
	v_lshlrev_b32_e32 v2, 12, v1
	v_and_b32_e32 v4, 0xff0, v4
	v_ashrrev_i32_e32 v7, 4, v32
	s_lshl_b32 s14, s16, 7
	s_ashr_i32 s23, s22, 31
	v_lshl_add_u32 v104, v1, 9, s0
	v_ashrrev_i32_e32 v1, 31, v0
	v_add_u32_e32 v13, 0, v3
	v_add3_u32 v101, 0, v2, v4
	v_lshlrev_b32_e32 v2, 5, v7
	s_add_i32 s15, s0, s14
	s_lshl_b64 s[22:23], s[22:23], 12
	v_readlane_b32 s17, v254, 14
	v_lshlrev_b64 v[0:1], 12, v[0:1]
	v_and_b32_e32 v3, 0xff, v32
	v_readlane_b32 s50, v254, 17
	v_readlane_b32 s51, v254, 18
	s_add_u32 s22, s17, s22
	v_readlane_b32 s17, v254, 31
	v_lshl_or_b32 v0, v3, 4, v0
	v_ashrrev_i32_e32 v3, 31, v2
	s_addc_u32 s23, s17, s23
	v_lshl_add_u64 v[86:87], s[50:51], 0, v[0:1]
	v_lshlrev_b64 v[0:1], 11, v[2:3]
	s_lshl_b32 s0, s16, 2
	v_lshlrev_b64 v[80:81], 2, v[32:33]
	v_readlane_b32 s52, v254, 19
	v_readlane_b32 s53, v254, 20
	v_readlane_b32 s56, v254, 23
	v_readlane_b32 s57, v254, 24
	v_lshl_add_u32 v94, v238, 4, 0
	v_mul_i32_i24_e32 v6, -12, v238
	v_lshl_add_u32 v8, v7, 8, 0
	v_lshlrev_b32_e32 v9, 4, v155
	v_lshlrev_b32_e32 v4, 4, v238
	v_mov_b32_e32 v5, v12
	v_lshl_or_b32 v0, v155, 4, v0
	s_add_i32 s17, s0, 0
	v_cmp_gt_i32_e64 s[38:39], 64, v32
	v_lshl_add_u64 v[82:83], s[52:53], 0, v[80:81]
	v_cmp_eq_u32_e64 s[40:41], 0, v238
	v_add_u32_e32 v103, 0x1f00, v32
	v_lshl_add_u64 v[84:85], s[22:23], 0, v[4:5]
	v_lshl_add_u64 v[88:89], s[56:57], 0, v[0:1]
	v_lshl_add_u32 v105, v7, 7, 0
	s_add_i32 s17, s17, 0x10100
	v_add_u32_e32 v106, v94, v6
	v_add_u32_e32 v107, v8, v9
	v_lshlrev_b32_e32 v108, 2, v238
	s_and_b32 s34, s78, 7
	s_lshl_b32 s34, s34, 4
	s_lshr_b32 s19, s78, 3
	s_or_b32 s34, s34, s19
	s_cmpk_lt_u32 s78, 0x80
	s_cselect_b32 s34, s34, s78
	s_cmpk_eq_u32 s10, 0x100
	s_cselect_b32 s34, s34, s78
	s_nop 0
	s_nop 0
	s_nop 0
	s_nop 0
	s_nop 0
	s_nop 0
	s_nop 0
	s_nop 0
	s_nop 0
	s_nop 0
	s_nop 0
	s_nop 0
	s_nop 0
	s_nop 0
	s_mov_b32 s19, s34
	v_readlane_b32 s54, v254, 21
	v_readlane_b32 s55, v254, 22
	v_readlane_b32 s58, v254, 25
	v_readlane_b32 s59, v254, 26
	v_readlane_b32 s60, v254, 27
	v_readlane_b32 s61, v254, 28
	v_readlane_b32 s62, v254, 29
	v_readlane_b32 s63, v254, 30
	s_branch .LBB0_96
	s_nop 0
	s_nop 0
	s_nop 0
	s_nop 0
	s_nop 0
	s_nop 0
	s_nop 0
	s_nop 0
	s_nop 0
	s_nop 0
	s_nop 0
	s_nop 0
	s_nop 0

; #define LAS __attribute__((address_space(3)))
; DI void tok0_mem(ldsp lds, const float* qm, const float* memb, const float* mnw, const float* Wkv, int hm, LAS float* out64, int tid, int wid, int lane) {
;     ...
;     if (tid < 64) QS[tid] = qm[tid];
;     __syncthreads();
; #pragma unroll
;     for (int h2 = 0; h2 < 2; ++h2) {
;         const int j = tid + h2 * 512; const float* wr = Wkv + (size_t)j * 512 + hm * 64; float t = 0.f;
; #pragma unroll
;         for (int d4 = 0; d4 < 16; ++d4) { const float4 w4 = *(const float4*)(wr + d4 * 4); const f32x4 q4 = *(LAS f32x4*)(QS + d4 * 4); t += w4.x * q4[0] + w4.y * q4[1] + w4.z * q4[2] + w4.w * q4[3]; }
;         U[j] = t * mnw[j];
.LBB0_96:
	s_ashr_i32 s52, s34, 2
	s_ashr_i32 s53, s52, 31
	s_and_b32 s35, s34, 3
	s_lshl_b64 s[50:51], s[52:53], 15
	v_readlane_b32 s22, v251, 25
	v_readlane_b32 s23, v251, 26
	s_add_u32 s54, s22, s50
	s_addc_u32 s55, s23, s51
	s_lshl_b32 s37, s35, 6
	v_mov_b64_e32 v[0:1], v[30:31]
	s_and_saveexec_b64 s[22:23], s[38:39]
	s_cbranch_execz .LBB0_98
	s_lshl_b32 s0, s37, 2
	s_add_u32 s26, s54, s0
	s_addc_u32 s27, s55, 0
	v_lshl_add_u64 v[0:1], v[32:33], 2, s[26:27]
	v_add_co_u32_e32 v0, vcc, 0x6000, v0
	s_nop 1
	v_addc_co_u32_e32 v1, vcc, 0, v1, vcc
	global_load_dword v4, v[0:1], off offset:3072
	v_mov_b64_e32 v[0:1], v[32:33]
.LBB0_98:
	s_or_b64 exec, exec, s[22:23]
	s_lshl_b64 s[26:27], s[52:53], 20
	s_lshl_b32 s36, s37, 2
	v_readlane_b32 s0, v251, 47
	s_add_u32 s30, s0, s36
	v_readlane_b32 s0, v251, 48
	s_addc_u32 s31, s0, 0
	v_lshlrev_b64 v[2:3], 11, v[0:1]
	v_lshl_add_u64 v[2:3], s[30:31], 0, v[2:3]
	v_readlane_b32 s56, v254, 15
	v_readlane_b32 s60, v254, 19
	v_readlane_b32 s61, v254, 20
	v_lshl_add_u64 v[92:93], v[84:85], 0, s[26:27]
	s_mov_b32 s0, -4
	v_lshl_add_u64 v[90:91], v[0:1], 2, s[60:61]
	v_readlane_b32 s57, v254, 16
	v_readlane_b32 s58, v254, 17
	v_readlane_b32 s59, v254, 18
	v_readlane_b32 s62, v254, 21
	v_readlane_b32 s63, v254, 22
	v_readlane_b32 s64, v254, 23
	v_readlane_b32 s65, v254, 24
	v_readlane_b32 s66, v254, 25
	v_readlane_b32 s67, v254, 26
	v_readlane_b32 s68, v254, 27
	v_readlane_b32 s69, v254, 28
	v_readlane_b32 s70, v254, 29
	v_readlane_b32 s71, v254, 30
	v_lshl_add_u64 v[246:247], s[30:31], 0, v[78:79]
	s_mov_b32 s30, s15
	global_load_dwordx4 v[158:161], v[2:3], off
	global_load_dwordx4 v[18:21], v[246:247], off
	global_load_dwordx4 v[162:165], v[2:3], off offset:16
	global_load_dwordx4 v[22:25], v[246:247], off offset:16
	global_load_dwordx4 v[166:169], v[2:3], off offset:32
	global_load_dwordx4 v[26:29], v[246:247], off offset:32
	global_load_dwordx4 v[170:173], v[2:3], off offset:48
	global_load_dwordx4 v[34:37], v[246:247], off offset:48
	global_load_dwordx4 v[174:177], v[2:3], off offset:64
	global_load_dwordx4 v[38:41], v[246:247], off offset:64
	global_load_dwordx4 v[178:181], v[2:3], off offset:80
	global_load_dwordx4 v[42:45], v[246:247], off offset:80
	global_load_dwordx4 v[182:185], v[2:3], off offset:96
	global_load_dwordx4 v[46:49], v[246:247], off offset:96
	global_load_dwordx4 v[186:189], v[2:3], off offset:112
	global_load_dwordx4 v[50:53], v[246:247], off offset:112
	global_load_dwordx4 v[190:193], v[2:3], off offset:128
	global_load_dwordx4 v[54:57], v[246:247], off offset:128
	global_load_dwordx4 v[194:197], v[2:3], off offset:144
	global_load_dwordx4 v[58:61], v[246:247], off offset:144
	global_load_dwordx4 v[198:201], v[2:3], off offset:160
	global_load_dwordx4 v[62:65], v[246:247], off offset:160
	global_load_dwordx4 v[202:205], v[2:3], off offset:176
	global_load_dwordx4 v[66:69], v[246:247], off offset:176
	global_load_dwordx4 v[206:209], v[2:3], off offset:192
	global_load_dwordx4 v[70:73], v[246:247], off offset:192
	global_load_dwordx4 v[210:213], v[2:3], off offset:208
	global_load_dwordx4 v[74:77], v[246:247], off offset:208
	global_load_dwordx4 v[214:217], v[2:3], off offset:224
	global_load_dwordx4 v[120:123], v[246:247], off offset:224
	global_load_dwordx4 v[218:221], v[2:3], off offset:240
	global_load_dwordx4 v[124:127], v[246:247], off offset:240
	global_load_dword v10, v[90:91], off
	global_load_dword v11, v[82:83], off offset:2048
	s_mov_b64 s[98:99], exec
	s_and_b64 exec, s[98:99], s[38:39]
	s_waitcnt vmcnt(34)
	ds_write_b32 v13, v4 offset:14336
	s_mov_b64 exec, s[98:99]
	s_waitcnt lgkmcnt(0)
	s_barrier
; #define LAS __attribute__((address_space(3)))
; DI void tok0_mem(ldsp lds, const float* qm, const float* memb, const float* mnw, const float* Wkv, int hm, LAS float* out64, int tid, int wid, int lane) {
;     ...
;     for (int h2 = 0; h2 < 2; ++h2) {
;         const int j = tid + h2 * 512; const float* wr = Wkv + (size_t)j * 512 + hm * 64; float t = 0.f;
; #pragma unroll
;         for (int d4 = 0; d4 < 16; ++d4) { const float4 w4 = *(const float4*)(wr + d4 * 4); const f32x4 q4 = *(LAS f32x4*)(QS + d4 * 4); t += w4.x * q4[0] + w4.y * q4[1] + w4.z * q4[2] + w4.w * q4[3]; }
;         U[j] = t * mnw[j];
;     }
;     __syncthreads();
	ds_read_b128 v[128:131], v12 offset:14336
	ds_read_b128 v[132:135], v12 offset:14352
	ds_read_b128 v[222:225], v12 offset:14368
	ds_read_b128 v[226:229], v12 offset:14384
	s_waitcnt vmcnt(26) lgkmcnt(0)
	v_mul_f32_e32 v6, v159, v129
	v_mul_f32_e32 v7, v19, v129
	v_fmac_f32_e32 v6, v158, v128
	v_fmac_f32_e32 v7, v18, v128
	v_fmac_f32_e32 v6, v160, v130
	v_fmac_f32_e32 v7, v20, v130
	v_fmac_f32_e32 v6, v161, v131
	v_fmac_f32_e32 v7, v21, v131
	v_add_f32_e32 v4, 0, v6
	v_add_f32_e32 v5, 0, v7
	v_mul_f32_e32 v6, v163, v133
	v_mul_f32_e32 v7, v23, v133
	v_fmac_f32_e32 v6, v162, v132
	v_fmac_f32_e32 v7, v22, v132
	v_fmac_f32_e32 v6, v164, v134
	v_fmac_f32_e32 v7, v24, v134
	v_fmac_f32_e32 v6, v165, v135
	v_fmac_f32_e32 v7, v25, v135
	v_add_f32_e32 v4, v4, v6
	v_add_f32_e32 v5, v5, v7
	v_mul_f32_e32 v6, v167, v223
	v_mul_f32_e32 v7, v27, v223
	v_fmac_f32_e32 v6, v166, v222
	v_fmac_f32_e32 v7, v26, v222
	v_fmac_f32_e32 v6, v168, v224
	v_fmac_f32_e32 v7, v28, v224
	v_fmac_f32_e32 v6, v169, v225
	v_fmac_f32_e32 v7, v29, v225
	v_add_f32_e32 v4, v4, v6
	v_add_f32_e32 v5, v5, v7
	v_mul_f32_e32 v6, v171, v227
	v_mul_f32_e32 v7, v35, v227
	v_fmac_f32_e32 v6, v170, v226
	v_fmac_f32_e32 v7, v34, v226
	v_fmac_f32_e32 v6, v172, v228
	v_fmac_f32_e32 v7, v36, v228
	v_fmac_f32_e32 v6, v173, v229
	v_fmac_f32_e32 v7, v37, v229
	v_add_f32_e32 v4, v4, v6
	v_add_f32_e32 v5, v5, v7
	ds_read_b128 v[128:131], v12 offset:14400
	ds_read_b128 v[132:135], v12 offset:14416
	ds_read_b128 v[222:225], v12 offset:14432
	ds_read_b128 v[226:229], v12 offset:14448
	s_waitcnt vmcnt(18) lgkmcnt(0)
	v_mul_f32_e32 v6, v175, v129
	v_mul_f32_e32 v7, v39, v129
	v_fmac_f32_e32 v6, v174, v128
	v_fmac_f32_e32 v7, v38, v128
	v_fmac_f32_e32 v6, v176, v130
	v_fmac_f32_e32 v7, v40, v130
	v_fmac_f32_e32 v6, v177, v131
	v_fmac_f32_e32 v7, v41, v131
	v_add_f32_e32 v4, v4, v6
	v_add_f32_e32 v5, v5, v7
	v_mul_f32_e32 v6, v179, v133
	v_mul_f32_e32 v7, v43, v133
	v_fmac_f32_e32 v6, v178, v132
	v_fmac_f32_e32 v7, v42, v132
	v_fmac_f32_e32 v6, v180, v134
	v_fmac_f32_e32 v7, v44, v134
	v_fmac_f32_e32 v6, v181, v135
	v_fmac_f32_e32 v7, v45, v135
	v_add_f32_e32 v4, v4, v6
	v_add_f32_e32 v5, v5, v7
	v_mul_f32_e32 v6, v183, v223
	v_mul_f32_e32 v7, v47, v223
	v_fmac_f32_e32 v6, v182, v222
	v_fmac_f32_e32 v7, v46, v222
	v_fmac_f32_e32 v6, v184, v224
	v_fmac_f32_e32 v7, v48, v224
	v_fmac_f32_e32 v6, v185, v225
	v_fmac_f32_e32 v7, v49, v225
	v_add_f32_e32 v4, v4, v6
	v_add_f32_e32 v5, v5, v7
	v_mul_f32_e32 v6, v187, v227
	v_mul_f32_e32 v7, v51, v227
	v_fmac_f32_e32 v6, v186, v226
	v_fmac_f32_e32 v7, v50, v226
	v_fmac_f32_e32 v6, v188, v228
	v_fmac_f32_e32 v7, v52, v228
	v_fmac_f32_e32 v6, v189, v229
	v_fmac_f32_e32 v7, v53, v229
	v_add_f32_e32 v4, v4, v6
	v_add_f32_e32 v5, v5, v7
	ds_read_b128 v[128:131], v12 offset:14464
	ds_read_b128 v[132:135], v12 offset:14480
	ds_read_b128 v[222:225], v12 offset:14496
	ds_read_b128 v[226:229], v12 offset:14512
	s_waitcnt vmcnt(10) lgkmcnt(0)
	v_mul_f32_e32 v6, v191, v129
	v_mul_f32_e32 v7, v55, v129
	v_fmac_f32_e32 v6, v190, v128
	v_fmac_f32_e32 v7, v54, v128
	v_fmac_f32_e32 v6, v192, v130
	v_fmac_f32_e32 v7, v56, v130
	v_fmac_f32_e32 v6, v193, v131
	v_fmac_f32_e32 v7, v57, v131
	v_add_f32_e32 v4, v4, v6
	v_add_f32_e32 v5, v5, v7
	v_mul_f32_e32 v6, v195, v133
	v_mul_f32_e32 v7, v59, v133
	v_fmac_f32_e32 v6, v194, v132
	v_fmac_f32_e32 v7, v58, v132
	v_fmac_f32_e32 v6, v196, v134
	v_fmac_f32_e32 v7, v60, v134
	v_fmac_f32_e32 v6, v197, v135
	v_fmac_f32_e32 v7, v61, v135
	v_add_f32_e32 v4, v4, v6
	v_add_f32_e32 v5, v5, v7
	v_mul_f32_e32 v6, v199, v223
	v_mul_f32_e32 v7, v63, v223
	v_fmac_f32_e32 v6, v198, v222
	v_fmac_f32_e32 v7, v62, v222
	v_fmac_f32_e32 v6, v200, v224
	v_fmac_f32_e32 v7, v64, v224
	v_fmac_f32_e32 v6, v201, v225
	v_fmac_f32_e32 v7, v65, v225
	v_add_f32_e32 v4, v4, v6
	v_add_f32_e32 v5, v5, v7
	v_mul_f32_e32 v6, v203, v227
	v_mul_f32_e32 v7, v67, v227
	v_fmac_f32_e32 v6, v202, v226
	v_fmac_f32_e32 v7, v66, v226
	v_fmac_f32_e32 v6, v204, v228
	v_fmac_f32_e32 v7, v68, v228
	v_fmac_f32_e32 v6, v205, v229
	v_fmac_f32_e32 v7, v69, v229
	v_add_f32_e32 v4, v4, v6
	v_add_f32_e32 v5, v5, v7
	ds_read_b128 v[128:131], v12 offset:14528
	ds_read_b128 v[132:135], v12 offset:14544
	ds_read_b128 v[222:225], v12 offset:14560
	ds_read_b128 v[226:229], v12 offset:14576
	s_waitcnt vmcnt(2) lgkmcnt(0)
	v_mul_f32_e32 v6, v207, v129
	v_mul_f32_e32 v7, v71, v129
	v_fmac_f32_e32 v6, v206, v128
	v_fmac_f32_e32 v7, v70, v128
	v_fmac_f32_e32 v6, v208, v130
	v_fmac_f32_e32 v7, v72, v130
	v_fmac_f32_e32 v6, v209, v131
	v_fmac_f32_e32 v7, v73, v131
	v_add_f32_e32 v4, v4, v6
	v_add_f32_e32 v5, v5, v7
	v_mul_f32_e32 v6, v211, v133
	v_mul_f32_e32 v7, v75, v133
	v_fmac_f32_e32 v6, v210, v132
	v_fmac_f32_e32 v7, v74, v132
	v_fmac_f32_e32 v6, v212, v134
	v_fmac_f32_e32 v7, v76, v134
	v_fmac_f32_e32 v6, v213, v135
	v_fmac_f32_e32 v7, v77, v135
	v_add_f32_e32 v4, v4, v6
	v_add_f32_e32 v5, v5, v7
	v_mul_f32_e32 v6, v215, v223
	v_mul_f32_e32 v7, v121, v223
	v_fmac_f32_e32 v6, v214, v222
	v_fmac_f32_e32 v7, v120, v222
	v_fmac_f32_e32 v6, v216, v224
	v_fmac_f32_e32 v7, v122, v224
	v_fmac_f32_e32 v6, v217, v225
	v_fmac_f32_e32 v7, v123, v225
	v_add_f32_e32 v4, v4, v6
	v_add_f32_e32 v5, v5, v7
	v_mul_f32_e32 v6, v219, v227
	v_mul_f32_e32 v7, v125, v227
	v_fmac_f32_e32 v6, v218, v226
	v_fmac_f32_e32 v7, v124, v226
	v_fmac_f32_e32 v6, v220, v228
	v_fmac_f32_e32 v7, v126, v228
	v_fmac_f32_e32 v6, v221, v229
	v_fmac_f32_e32 v7, v127, v229
	v_add_f32_e32 v4, v4, v6
	v_add_f32_e32 v5, v5, v7
	s_waitcnt vmcnt(1)
	v_mul_f32_e32 v10, v10, v4
	ds_write_b32 v13, v10
	s_waitcnt vmcnt(0)
	v_mul_f32_e32 v11, v11, v5
	ds_write_b32 v13, v11 offset:2048
	s_waitcnt lgkmcnt(0)
	s_barrier
	ds_read_b128 v[0:3], v94
	ds_read_b128 v[4:7], v94 offset:1024
	ds_read_b128 v[8:11], v94 offset:2048
	ds_read_b128 v[14:17], v94 offset:3072
	s_branch .Lp2_entry_s5

; #define LAS __attribute__((address_space(3)))
; DI void tok0_mem(ldsp lds, const float* qm, const float* memb, const float* mnw, const float* Wkv, int hm, LAS float* out64, int tid, int wid, int lane) {
;     ...
;     if (tid < 64) QS[tid] = qm[tid];
;     __syncthreads();
; #pragma unroll
;     for (int h2 = 0; h2 < 2; ++h2) {
;         const int j = tid + h2 * 512; const float* wr = Wkv + (size_t)j * 512 + hm * 64; float t = 0.f;
; #pragma unroll
;         for (int d4 = 0; d4 < 16; ++d4) { const float4 w4 = *(const float4*)(wr + d4 * 4); const f32x4 q4 = *(LAS f32x4*)(QS + d4 * 4); t += w4.x * q4[0] + w4.y * q4[1] + w4.z * q4[2] + w4.w * q4[3]; }
;         U[j] = t * mnw[j];
.LBB0_830:
	s_ashr_i32 s46, s36, 2
	s_ashr_i32 s47, s46, 31
	s_and_b32 s37, s36, 3
	s_lshl_b64 s[22:23], s[46:47], 15
	v_readlane_b32 s26, v251, 25
	v_readlane_b32 s27, v251, 26
	s_add_u32 s48, s26, s22
	s_addc_u32 s49, s27, s23
	s_lshl_b32 s51, s37, 6
	v_mov_b64_e32 v[0:1], v[30:31]
	s_and_saveexec_b64 s[22:23], s[38:39]
	s_cbranch_execz .LBB0_832
	s_lshl_b32 s0, s51, 2
	s_add_u32 s26, s48, s0
	s_addc_u32 s27, s49, 0
	v_lshl_add_u64 v[0:1], v[32:33], 2, s[26:27]
	v_add_co_u32_e32 v0, vcc, 0x1000, v0
	s_nop 1
	v_addc_co_u32_e32 v1, vcc, 0, v1, vcc
	global_load_dword v4, v[0:1], off offset:2112
	v_mov_b64_e32 v[0:1], v[32:33]
.LBB0_832:
	s_or_b64 exec, exec, s[22:23]
	v_readlane_b32 s52, v254, 15
	s_lshl_b64 s[26:27], s[46:47], 20
	s_lshl_b32 s50, s51, 2
	v_readlane_b32 s60, v254, 23
	v_readlane_b32 s61, v254, 24
	s_add_u32 s30, s60, s50
	s_addc_u32 s31, s61, 0
	v_lshlrev_b64 v[2:3], 11, v[0:1]
	v_lshl_add_u64 v[2:3], s[30:31], 0, v[2:3]
	v_readlane_b32 s56, v254, 19
	v_readlane_b32 s57, v254, 20
	v_lshl_add_u64 v[94:95], v[84:85], 0, s[26:27]
	s_mov_b32 s0, -4
	v_lshl_add_u64 v[92:93], v[0:1], 2, s[56:57]
	v_readlane_b32 s53, v254, 16
	v_readlane_b32 s54, v254, 17
	v_readlane_b32 s55, v254, 18
	v_readlane_b32 s58, v254, 21
	v_readlane_b32 s59, v254, 22
	v_readlane_b32 s62, v254, 25
	v_readlane_b32 s63, v254, 26
	v_readlane_b32 s64, v254, 27
	v_readlane_b32 s65, v254, 28
	v_readlane_b32 s66, v254, 29
	v_readlane_b32 s67, v254, 30
	v_lshl_add_u64 v[246:247], s[30:31], 0, v[78:79]
	s_mov_b32 s30, s34
	global_load_dwordx4 v[158:161], v[2:3], off
	global_load_dwordx4 v[18:21], v[246:247], off
	global_load_dwordx4 v[162:165], v[2:3], off offset:16
	global_load_dwordx4 v[22:25], v[246:247], off offset:16
	global_load_dwordx4 v[166:169], v[2:3], off offset:32
	global_load_dwordx4 v[26:29], v[246:247], off offset:32
	global_load_dwordx4 v[170:173], v[2:3], off offset:48
	global_load_dwordx4 v[34:37], v[246:247], off offset:48
	global_load_dwordx4 v[174:177], v[2:3], off offset:64
	global_load_dwordx4 v[38:41], v[246:247], off offset:64
	global_load_dwordx4 v[178:181], v[2:3], off offset:80
	global_load_dwordx4 v[42:45], v[246:247], off offset:80
	global_load_dwordx4 v[182:185], v[2:3], off offset:96
	global_load_dwordx4 v[46:49], v[246:247], off offset:96
	global_load_dwordx4 v[186:189], v[2:3], off offset:112
	global_load_dwordx4 v[50:53], v[246:247], off offset:112
	global_load_dwordx4 v[190:193], v[2:3], off offset:128
	global_load_dwordx4 v[54:57], v[246:247], off offset:128
	global_load_dwordx4 v[194:197], v[2:3], off offset:144
	global_load_dwordx4 v[58:61], v[246:247], off offset:144
	global_load_dwordx4 v[198:201], v[2:3], off offset:160
	global_load_dwordx4 v[62:65], v[246:247], off offset:160
	global_load_dwordx4 v[202:205], v[2:3], off offset:176
	global_load_dwordx4 v[66:69], v[246:247], off offset:176
	global_load_dwordx4 v[206:209], v[2:3], off offset:192
	global_load_dwordx4 v[70:73], v[246:247], off offset:192
	global_load_dwordx4 v[210:213], v[2:3], off offset:208
	global_load_dwordx4 v[74:77], v[246:247], off offset:208
	global_load_dwordx4 v[214:217], v[2:3], off offset:224
	global_load_dwordx4 v[120:123], v[246:247], off offset:224
	global_load_dwordx4 v[218:221], v[2:3], off offset:240
	global_load_dwordx4 v[124:127], v[246:247], off offset:240
	global_load_dword v10, v[92:93], off
	global_load_dword v11, v[80:81], off offset:2048
	s_mov_b64 s[98:99], exec
	s_and_b64 exec, s[98:99], s[38:39]
	s_waitcnt vmcnt(34)
	ds_write_b32 v13, v4 offset:14336
	s_mov_b64 exec, s[98:99]
	s_waitcnt lgkmcnt(0)
	s_barrier
; #define LAS __attribute__((address_space(3)))
; DI void tok0_mem(ldsp lds, const float* qm, const float* memb, const float* mnw, const float* Wkv, int hm, LAS float* out64, int tid, int wid, int lane) {
;     ...
;     for (int h2 = 0; h2 < 2; ++h2) {
;         const int j = tid + h2 * 512; const float* wr = Wkv + (size_t)j * 512 + hm * 64; float t = 0.f;
; #pragma unroll
;         for (int d4 = 0; d4 < 16; ++d4) { const float4 w4 = *(const float4*)(wr + d4 * 4); const f32x4 q4 = *(LAS f32x4*)(QS + d4 * 4); t += w4.x * q4[0] + w4.y * q4[1] + w4.z * q4[2] + w4.w * q4[3]; }
;         U[j] = t * mnw[j];
;     }
;     __syncthreads();
	ds_read_b128 v[128:131], v12 offset:14336
	ds_read_b128 v[132:135], v12 offset:14352
	ds_read_b128 v[222:225], v12 offset:14368
	ds_read_b128 v[226:229], v12 offset:14384
	s_waitcnt vmcnt(26) lgkmcnt(0)
	v_mul_f32_e32 v6, v159, v129
	v_mul_f32_e32 v7, v19, v129
	v_fmac_f32_e32 v6, v158, v128
	v_fmac_f32_e32 v7, v18, v128
	v_fmac_f32_e32 v6, v160, v130
	v_fmac_f32_e32 v7, v20, v130
	v_fmac_f32_e32 v6, v161, v131
	v_fmac_f32_e32 v7, v21, v131
	v_add_f32_e32 v4, 0, v6
	v_add_f32_e32 v5, 0, v7
	v_mul_f32_e32 v6, v163, v133
	v_mul_f32_e32 v7, v23, v133
	v_fmac_f32_e32 v6, v162, v132
	v_fmac_f32_e32 v7, v22, v132
	v_fmac_f32_e32 v6, v164, v134
	v_fmac_f32_e32 v7, v24, v134
	v_fmac_f32_e32 v6, v165, v135
	v_fmac_f32_e32 v7, v25, v135
	v_add_f32_e32 v4, v4, v6
	v_add_f32_e32 v5, v5, v7
	v_mul_f32_e32 v6, v167, v223
	v_mul_f32_e32 v7, v27, v223
	v_fmac_f32_e32 v6, v166, v222
	v_fmac_f32_e32 v7, v26, v222
	v_fmac_f32_e32 v6, v168, v224
	v_fmac_f32_e32 v7, v28, v224
	v_fmac_f32_e32 v6, v169, v225
	v_fmac_f32_e32 v7, v29, v225
	v_add_f32_e32 v4, v4, v6
	v_add_f32_e32 v5, v5, v7
	v_mul_f32_e32 v6, v171, v227
	v_mul_f32_e32 v7, v35, v227
	v_fmac_f32_e32 v6, v170, v226
	v_fmac_f32_e32 v7, v34, v226
	v_fmac_f32_e32 v6, v172, v228
	v_fmac_f32_e32 v7, v36, v228
	v_fmac_f32_e32 v6, v173, v229
	v_fmac_f32_e32 v7, v37, v229
	v_add_f32_e32 v4, v4, v6
	v_add_f32_e32 v5, v5, v7
	ds_read_b128 v[128:131], v12 offset:14400
	ds_read_b128 v[132:135], v12 offset:14416
	ds_read_b128 v[222:225], v12 offset:14432
	ds_read_b128 v[226:229], v12 offset:14448
	s_waitcnt vmcnt(18) lgkmcnt(0)
	v_mul_f32_e32 v6, v175, v129
	v_mul_f32_e32 v7, v39, v129
	v_fmac_f32_e32 v6, v174, v128
	v_fmac_f32_e32 v7, v38, v128
	v_fmac_f32_e32 v6, v176, v130
	v_fmac_f32_e32 v7, v40, v130
	v_fmac_f32_e32 v6, v177, v131
	v_fmac_f32_e32 v7, v41, v131
	v_add_f32_e32 v4, v4, v6
	v_add_f32_e32 v5, v5, v7
	v_mul_f32_e32 v6, v179, v133
	v_mul_f32_e32 v7, v43, v133
	v_fmac_f32_e32 v6, v178, v132
	v_fmac_f32_e32 v7, v42, v132
	v_fmac_f32_e32 v6, v180, v134
	v_fmac_f32_e32 v7, v44, v134
	v_fmac_f32_e32 v6, v181, v135
	v_fmac_f32_e32 v7, v45, v135
	v_add_f32_e32 v4, v4, v6
	v_add_f32_e32 v5, v5, v7
	v_mul_f32_e32 v6, v183, v223
	v_mul_f32_e32 v7, v47, v223
	v_fmac_f32_e32 v6, v182, v222
	v_fmac_f32_e32 v7, v46, v222
	v_fmac_f32_e32 v6, v184, v224
	v_fmac_f32_e32 v7, v48, v224
	v_fmac_f32_e32 v6, v185, v225
	v_fmac_f32_e32 v7, v49, v225
	v_add_f32_e32 v4, v4, v6
	v_add_f32_e32 v5, v5, v7
	v_mul_f32_e32 v6, v187, v227
	v_mul_f32_e32 v7, v51, v227
	v_fmac_f32_e32 v6, v186, v226
	v_fmac_f32_e32 v7, v50, v226
	v_fmac_f32_e32 v6, v188, v228
	v_fmac_f32_e32 v7, v52, v228
	v_fmac_f32_e32 v6, v189, v229
	v_fmac_f32_e32 v7, v53, v229
	v_add_f32_e32 v4, v4, v6
	v_add_f32_e32 v5, v5, v7
	ds_read_b128 v[128:131], v12 offset:14464
	ds_read_b128 v[132:135], v12 offset:14480
	ds_read_b128 v[222:225], v12 offset:14496
	ds_read_b128 v[226:229], v12 offset:14512
	s_waitcnt vmcnt(10) lgkmcnt(0)
	v_mul_f32_e32 v6, v191, v129
	v_mul_f32_e32 v7, v55, v129
	v_fmac_f32_e32 v6, v190, v128
	v_fmac_f32_e32 v7, v54, v128
	v_fmac_f32_e32 v6, v192, v130
	v_fmac_f32_e32 v7, v56, v130
	v_fmac_f32_e32 v6, v193, v131
	v_fmac_f32_e32 v7, v57, v131
	v_add_f32_e32 v4, v4, v6
	v_add_f32_e32 v5, v5, v7
	v_mul_f32_e32 v6, v195, v133
	v_mul_f32_e32 v7, v59, v133
	v_fmac_f32_e32 v6, v194, v132
	v_fmac_f32_e32 v7, v58, v132
	v_fmac_f32_e32 v6, v196, v134
	v_fmac_f32_e32 v7, v60, v134
	v_fmac_f32_e32 v6, v197, v135
	v_fmac_f32_e32 v7, v61, v135
	v_add_f32_e32 v4, v4, v6
	v_add_f32_e32 v5, v5, v7
	v_mul_f32_e32 v6, v199, v223
	v_mul_f32_e32 v7, v63, v223
	v_fmac_f32_e32 v6, v198, v222
	v_fmac_f32_e32 v7, v62, v222
	v_fmac_f32_e32 v6, v200, v224
	v_fmac_f32_e32 v7, v64, v224
	v_fmac_f32_e32 v6, v201, v225
	v_fmac_f32_e32 v7, v65, v225
	v_add_f32_e32 v4, v4, v6
	v_add_f32_e32 v5, v5, v7
	v_mul_f32_e32 v6, v203, v227
	v_mul_f32_e32 v7, v67, v227
	v_fmac_f32_e32 v6, v202, v226
	v_fmac_f32_e32 v7, v66, v226
	v_fmac_f32_e32 v6, v204, v228
	v_fmac_f32_e32 v7, v68, v228
	v_fmac_f32_e32 v6, v205, v229
	v_fmac_f32_e32 v7, v69, v229
	v_add_f32_e32 v4, v4, v6
	v_add_f32_e32 v5, v5, v7
	ds_read_b128 v[128:131], v12 offset:14528
	ds_read_b128 v[132:135], v12 offset:14544
	ds_read_b128 v[222:225], v12 offset:14560
	ds_read_b128 v[226:229], v12 offset:14576
	s_waitcnt vmcnt(2) lgkmcnt(0)
	v_mul_f32_e32 v6, v207, v129
	v_mul_f32_e32 v7, v71, v129
	v_fmac_f32_e32 v6, v206, v128
	v_fmac_f32_e32 v7, v70, v128
	v_fmac_f32_e32 v6, v208, v130
	v_fmac_f32_e32 v7, v72, v130
	v_fmac_f32_e32 v6, v209, v131
	v_fmac_f32_e32 v7, v73, v131
	v_add_f32_e32 v4, v4, v6
	v_add_f32_e32 v5, v5, v7
	v_mul_f32_e32 v6, v211, v133
	v_mul_f32_e32 v7, v75, v133
	v_fmac_f32_e32 v6, v210, v132
	v_fmac_f32_e32 v7, v74, v132
	v_fmac_f32_e32 v6, v212, v134
	v_fmac_f32_e32 v7, v76, v134
	v_fmac_f32_e32 v6, v213, v135
	v_fmac_f32_e32 v7, v77, v135
	v_add_f32_e32 v4, v4, v6
	v_add_f32_e32 v5, v5, v7
	v_mul_f32_e32 v6, v215, v223
	v_mul_f32_e32 v7, v121, v223
	v_fmac_f32_e32 v6, v214, v222
	v_fmac_f32_e32 v7, v120, v222
	v_fmac_f32_e32 v6, v216, v224
	v_fmac_f32_e32 v7, v122, v224
	v_fmac_f32_e32 v6, v217, v225
	v_fmac_f32_e32 v7, v123, v225
	v_add_f32_e32 v4, v4, v6
	v_add_f32_e32 v5, v5, v7
	v_mul_f32_e32 v6, v219, v227
	v_mul_f32_e32 v7, v125, v227
	v_fmac_f32_e32 v6, v218, v226
	v_fmac_f32_e32 v7, v124, v226
	v_fmac_f32_e32 v6, v220, v228
	v_fmac_f32_e32 v7, v126, v228
	v_fmac_f32_e32 v6, v221, v229
	v_fmac_f32_e32 v7, v127, v229
	v_add_f32_e32 v4, v4, v6
	v_add_f32_e32 v5, v5, v7
	s_waitcnt vmcnt(1)
	v_mul_f32_e32 v10, v10, v4
	ds_write_b32 v13, v10
	s_waitcnt vmcnt(0)
	v_mul_f32_e32 v11, v11, v5
	ds_write_b32 v13, v11 offset:2048
	s_waitcnt lgkmcnt(0)
	s_barrier
	ds_read_b128 v[0:3], v96
	ds_read_b128 v[4:7], v96 offset:1024
	ds_read_b128 v[8:11], v96 offset:2048
	ds_read_b128 v[14:17], v96 offset:3072
	s_branch .Lp2_entry_s2

; __global__ void __launch_bounds__(NTHREADS, 2) megak(Params p) {
;     ...
;                 if (L == 0) for (int t = blockIdx.x; t < BATCH * 4; t += gridDim.x) tok0_mix_gla(lds, p, T0P, T0BR, t, tid, wid, lane);
.LBB0_860:
	s_nop 0
	s_nop 0
	s_nop 0
	s_nop 0
	s_nop 0
	s_nop 0
	s_nop 0
	s_nop 0
	s_nop 0
	s_nop 0
	s_nop 0
	s_nop 0
	s_nop 0
	s_nop 0
	s_nop 0
	s_mov_b64 s[22:23], 0
